# st3 split variant: ssd_z only for blocks 0-3, four rowfin items for blocks 4-7
# baseline (speedup 1.0000x reference)
.LBB0_798:
	s_andn2_b64 vcc, exec, s[2:3]
	s_cbranch_vccnz .LBB0_1364
	v_readlane_b32 s0, v255, 46
	s_cmp_lt_i32 s0, 2
	s_mov_b64 s[2:3], -1
	s_cbranch_scc1 .LBB0_873
	v_readlane_b32 s0, v255, 46
	s_cmp_gt_i32 s0, 2
	s_cbranch_scc0 .LBB0_809
	s_cmpk_gt_i32 s45, 0x4ff
	s_mov_b32 s29, 0x6bb9000
	s_cbranch_scc1 .LBB0_808
	s_add_u32 s4, s82, 0xa3b9000
	s_addc_u32 s5, s83, 0
	s_add_u32 s6, s82, 0xe3b9000
	s_addc_u32 s7, s83, 0
	s_add_u32 s8, s82, 0x10bb9000
	s_addc_u32 s9, s83, 0
	s_add_u32 s10, s82, 0x113b9000
	s_addc_u32 s11, s83, 0
	s_add_u32 s12, s82, 0x6a31000
	s_addc_u32 s13, s83, 0
	s_add_u32 s14, s82, 0x103b9000
	s_addc_u32 s15, s83, 0
	s_add_u32 s16, s82, 0x69b0000
	s_addc_u32 s17, s83, 0
	s_and_b32 s0, s45, 1
	s_lshl_b32 s1, s0, 7
	s_add_u32 s2, s82, s1
	s_addc_u32 s3, s83, 0
	s_add_u32 s18, s2, 0x107b9000
	s_addc_u32 s19, s3, 0
	s_lshl_b32 s22, s0, 1
	s_lshl_b32 s0, s0, 8
	s_add_u32 s0, s82, s0
	s_addc_u32 s2, s83, 0
	s_add_u32 s20, s0, 0xf3b9000
	s_addc_u32 s21, s2, 0
	s_lshl_b32 s0, s45, 4
	s_or_b32 s23, s22, 1
	s_add_i32 s27, s0, 0xfffff000
	s_lshl_b32 s30, s78, 5
	s_lshl_b32 s52, s1, 1
	s_mov_b32 s31, s45
	s_cmpk_lg_u32 s80, 0x200
	s_cbranch_scc1 .Lst3_i_done
	s_lshr_b32 s33, s45, 1
	s_and_b32 s34, s33, 7
	s_lshl_b32 s34, s34, 3
	s_lshr_b32 s35, s33, 5
	s_add_i32 s34, s34, s35
	s_bfe_u32 s35, s33, 0x20003
	s_lshl_b32 s35, s35, 1
	s_and_b32 s33, s45, 1
	s_add_i32 s35, s35, s33
	s_lshl_b32 s32, s34, 4
	s_addk_i32 s32, 0x100
	s_lshl_b32 s33, s35, 2
	s_add_i32 s33, s33, -16
	s_add_i32 s32, s32, s33
	s_add_i32 s33, s32, 3
	s_lshl_b32 s34, s34, 2
	s_add_i32 s31, s34, s35
	s_cmp_lt_u32 s35, 4
	s_cselect_b32 s31, s31, s32
	s_lshl_b32 s27, s31, 4
	s_add_i32 s27, s27, 0xfffff000
